# A-loop DMA blocks: m0 written two instructions ahead of the LDS-DMA so the hazard s_nop is dropped (on top of A DMA restructure)
# speedup vs baseline: 1.0009x; 1.0009x over previous
.LBB0_557:
	ds_read_b128 v[32:35], v199 offset:20480
	ds_read_b128 v[42:45], v199 offset:24576
	s_mov_b32 m0, s9
	s_add_u32 s4, s92, 0x15648000
	s_addc_u32 s5, s93, 0
	global_load_lds_dwordx4 v164, s[4:5]
	s_waitcnt lgkmcnt(0)
	v_mfma_f32_32x32x16_bf16 v[112:127], v[32:35], v[132:135], v[48:63]
	ds_read_b128 v[38:41], v200 offset:20480
	ds_read_b128 v[188:191], v200 offset:24576
	s_setprio 1
	v_exp_f32_e32 v34, v80
	v_exp_f32_e32 v37, v81
	v_exp_f32_e32 v36, v82
	v_exp_f32_e32 v35, v83
	s_setprio 0
	s_mov_b32 m0, s7
	s_add_u32 s4, s92, 0x16618180
	s_addc_u32 s5, s93, 0
	global_load_lds_dwordx4 v160, s[4:5]
	s_waitcnt lgkmcnt(0)
	v_mfma_f32_32x32x16_bf16 v[112:127], v[38:41], v[128:131], v[112:127]
	ds_read_b128 v[80:83], v201 offset:20480
	ds_read_b128 v[220:223], v201 offset:24576
	s_setprio 1
	v_mfma_f32_32x32x16_bf16 v[96:111], v[42:45], v[132:135], v[48:63]
	v_exp_f32_e32 v32, v84
	v_exp_f32_e32 v41, v85
	v_exp_f32_e32 v40, v86
	v_exp_f32_e32 v33, v87
	s_setprio 0
	v_cvt_pk_bf16_f32 v84, v34, v37
	v_cvt_pk_bf16_f32 v85, v36, v35
	v_cvt_pk_bf16_f32 v86, v32, v41
	v_cvt_pk_bf16_f32 v87, v40, v33
	s_and_b64 vcc, exec, s[44:45]
	s_cbranch_vccnz .Lmy_a1_norope
	s_mov_b32 m0, s6
	s_add_u32 s4, s92, 0x30e8500
	s_addc_u32 s5, s93, 0
	global_load_lds_dwordx4 v162, s[4:5]

.LBB0_564:
.LBB0_566:
	ds_read_b128 v[64:67], v199 offset:40960
	ds_read_b128 v[220:223], v199 offset:45056
	s_mov_b32 m0, s43
	s_add_u32 s4, s92, 0x15658000
	s_addc_u32 s5, s93, 0
	global_load_lds_dwordx4 v164, s[4:5]
	s_waitcnt lgkmcnt(0)
	v_mfma_f32_32x32x16_bf16 v[80:95], v[64:67], v[132:135], v[32:47]
	ds_read_b128 v[68:71], v200 offset:40960
	ds_read_b128 v[224:227], v200 offset:45056
	s_setprio 1
	v_exp_f32_e32 v112, v112
	v_exp_f32_e32 v189, v113
	v_exp_f32_e32 v188, v114
	v_exp_f32_e32 v113, v115
	s_setprio 0
	s_mov_b32 m0, s70
	s_add_u32 s4, s92, 0x16618200
	s_addc_u32 s5, s93, 0
	global_load_lds_dwordx4 v160, s[4:5]
	s_waitcnt lgkmcnt(0)
	v_mfma_f32_32x32x16_bf16 v[80:95], v[68:71], v[128:131], v[80:95]
	ds_read_b128 v[228:231], v201 offset:40960
	ds_read_b128 v[232:235], v201 offset:45056
	s_setprio 1
	v_mfma_f32_32x32x16_bf16 v[64:79], v[220:223], v[132:135], v[32:47]
	v_exp_f32_e32 v114, v116
	v_exp_f32_e32 v117, v117
	v_exp_f32_e32 v116, v118
	v_exp_f32_e32 v115, v119
	s_setprio 0
	v_cvt_pk_bf16_f32 v220, v112, v189
	v_cvt_pk_bf16_f32 v221, v188, v113
	v_cvt_pk_bf16_f32 v222, v114, v117
	v_cvt_pk_bf16_f32 v223, v116, v115
	s_and_b64 vcc, exec, s[44:45]
	s_cbranch_vccnz .Lmy_a2_norope
	s_add_i32 m0, s43, 0x4000
	s_add_u32 s4, s92, 0x31d8500
	s_addc_u32 s5, s93, 0
	global_load_lds_dwordx4 v162, s[4:5]

.LBB0_572:
.LBB0_574:
	s_add_i32 s10, 0, 0x10000
	v_add_u32_e32 v172, s10, v212
	ds_read_b128 v[96:99], v199 offset:61440
	ds_read_b128 v[174:177], v172
	s_mov_b32 m0, s71
	s_add_u32 s4, s92, 0x15668000
	s_addc_u32 s5, s93, 0
	global_load_lds_dwordx4 v164, s[4:5]
	s_waitcnt lgkmcnt(0)
	v_mfma_f32_32x32x16_bf16 v[112:127], v[96:99], v[132:135], v[32:47]
	v_add_u32_e32 v220, s10, v214
	ds_read_b128 v[100:103], v200 offset:61440
	ds_read_b128 v[180:183], v220
	s_setprio 1
	v_exp_f32_e32 v80, v80
	v_exp_f32_e32 v189, v81
	v_exp_f32_e32 v188, v82
	v_exp_f32_e32 v81, v83
	s_setprio 0
	s_mov_b32 m0, s90
	s_add_u32 s4, s92, 0x16618280
	s_addc_u32 s5, s93, 0
	global_load_lds_dwordx4 v160, s[4:5]
	s_waitcnt lgkmcnt(0)
	v_mfma_f32_32x32x16_bf16 v[112:127], v[100:103], v[128:131], v[112:127]
	v_add_u32_e32 v221, s10, v216
	ds_read_b128 v[224:227], v201 offset:61440
	ds_read_b128 v[228:231], v221
	s_setprio 1
	v_mfma_f32_32x32x16_bf16 v[96:111], v[174:177], v[132:135], v[32:47]
	v_exp_f32_e32 v82, v84
	v_exp_f32_e32 v191, v85
	v_exp_f32_e32 v190, v86
	v_exp_f32_e32 v83, v87
	s_setprio 0
	v_cvt_pk_bf16_f32 v174, v80, v189
	v_cvt_pk_bf16_f32 v175, v188, v81
	v_cvt_pk_bf16_f32 v176, v82, v191
	v_cvt_pk_bf16_f32 v177, v190, v83
	s_and_b64 vcc, exec, s[44:45]
	s_cbranch_vccnz .Lmy_a3_norope
	s_add_i32 m0, s43, 0x9000
	s_add_u32 s4, s92, 0x32c8500
	s_addc_u32 s5, s93, 0
	global_load_lds_dwordx4 v162, s[4:5]

.LBB0_580:
.LBB0_582:
	ds_read_b128 v[64:67], v199
	ds_read_b128 v[174:177], v199 offset:4096
	s_mov_b32 m0, s91
	s_add_u32 s4, s92, 0x15678000
	s_addc_u32 s5, s93, 0
	global_load_lds_dwordx4 v164, s[4:5]
	s_waitcnt lgkmcnt(0)
	v_mfma_f32_32x32x16_bf16 v[80:95], v[64:67], v[132:135], v[32:47]
	ds_read_b128 v[68:71], v200
	ds_read_b128 v[180:183], v200 offset:4096
	s_setprio 1
	v_exp_f32_e32 v112, v112
	v_exp_f32_e32 v167, v113
	v_exp_f32_e32 v166, v114
	v_exp_f32_e32 v113, v115
	s_setprio 0
	s_mov_b32 m0, s95
	s_add_u32 s4, s92, 0x16618300
	s_addc_u32 s5, s93, 0
	global_load_lds_dwordx4 v160, s[4:5]
	s_waitcnt lgkmcnt(0)
	v_mfma_f32_32x32x16_bf16 v[80:95], v[68:71], v[128:131], v[80:95]
	ds_read_b128 v[188:191], v201
	ds_read_b128 v[192:195], v201 offset:4096
	s_setprio 1
	v_mfma_f32_32x32x16_bf16 v[64:79], v[174:177], v[132:135], v[32:47]
	v_exp_f32_e32 v114, v116
	v_exp_f32_e32 v169, v117
	v_exp_f32_e32 v168, v118
	v_exp_f32_e32 v115, v119
	s_setprio 0
	v_cvt_pk_bf16_f32 v174, v112, v167
	v_cvt_pk_bf16_f32 v175, v166, v113
	v_cvt_pk_bf16_f32 v176, v114, v169
	v_cvt_pk_bf16_f32 v177, v168, v115
	s_and_b64 vcc, exec, s[44:45]
	s_cbranch_vccnz .Lmy_a4_norope
	s_add_i32 m0, s43, 0xe000
	s_add_u32 s4, s92, 0x33b8500
	s_addc_u32 s5, s93, 0
	global_load_lds_dwordx4 v162, s[4:5]
